# v71 + attention output stores widened (v_permlane32_swap pairs, 8x dwordx4 instead of 16x dwordx2) + fast-loop back edge rotated ahead of the barrier
# baseline (speedup 1.0000x reference)
.LBB0_1318:
	s_sub_i32 s33, s33, 64
	s_sub_i32 s93, s93, 64
	s_add_u32 s90, s90, 0xffffffc0
	s_addc_u32 s91, s91, -1
	s_add_u32 s72, s72, 0x20000
	s_addc_u32 s73, s73, 0
	s_add_i32 s4, s95, 1
	s_cmp_eq_u32 s95, s70
	v_add_u32_e32 v179, 64, v179
	s_cbranch_scc1 .LBB0_1320
	s_mov_b32 s8, s78
	s_mov_b32 s78, s88
	s_mov_b32 s88, s71
	s_mov_b32 s95, s4
	s_branch .LBB0_1304
.Latt_flA_top:
	s_waitcnt vmcnt(4) lgkmcnt(0)
	s_barrier
.Latt_flA_entry:
	s_lshl_b32 s6, s8, 14
	v_add_u32_e32 v228, s6, v163
	v_add_u32_e32 v229, s6, v164
	v_add_u32_e32 v230, s6, v165
	v_add_u32_e32 v231, s6, v166
	ds_read_b128 v[96:99], v228
	ds_read_b128 v[200:203], v229
	ds_read_b128 v[204:207], v230
	ds_read_b128 v[208:211], v231
	ds_read_b128 v[112:115], v228 offset:8192
	ds_read_b128 v[216:219], v229 offset:8192
	ds_read_b128 v[220:223], v230 offset:8192
	ds_read_b128 v[224:227], v231 offset:8192
	s_add_u32 s98, s0, s72
	s_addc_u32 s99, s1, s73
	s_lshl_b32 s4, s88, 14
	s_add_i32 s5, s87, s4
	s_mov_b32 m0, s5
	s_add_i32 s4, s95, 2
	s_and_b32 s4, s4, 3
	s_lshl_b32 s4, s4, 14
	s_add_i32 s4, s85, s4
	s_waitcnt lgkmcnt(7)
	v_mfma_f32_32x32x16_bf16 v[96:111], v[96:99], v[132:135], 0
	s_waitcnt lgkmcnt(6)
	v_mfma_f32_32x32x16_bf16 v[96:111], v[200:203], v[136:139], v[96:111]
	s_waitcnt lgkmcnt(5)
	v_mfma_f32_32x32x16_bf16 v[96:111], v[204:207], v[140:143], v[96:111]
	s_waitcnt lgkmcnt(4)
	v_mfma_f32_32x32x16_bf16 v[96:111], v[208:211], v[144:147], v[96:111]
	s_waitcnt lgkmcnt(3)
	v_mfma_f32_32x32x16_bf16 v[112:127], v[112:115], v[132:135], 0
	global_load_lds_dwordx4 v239, s[98:99]
	s_addk_i32 s5, 0x400
	s_mov_b32 m0, s5
	s_waitcnt lgkmcnt(2)
	v_mfma_f32_32x32x16_bf16 v[112:127], v[216:219], v[136:139], v[112:127]
	global_load_lds_dwordx4 v240, s[98:99]
	s_add_u32 s98, s66, s72
	s_addc_u32 s99, s67, s73
	s_mov_b32 m0, s4
	s_addk_i32 s4, 0x400
	s_waitcnt lgkmcnt(1)
	v_mfma_f32_32x32x16_bf16 v[112:127], v[220:223], v[140:143], v[112:127]
	global_load_lds_dwordx4 v241, s[98:99]
	s_mov_b32 m0, s4
	s_waitcnt lgkmcnt(0)
	v_mfma_f32_32x32x16_bf16 v[112:127], v[224:227], v[144:147], v[112:127]
	global_load_lds_dwordx4 v242, s[98:99]
	s_and_b32 s7, s95, 3
	s_lshl_b32 s7, s7, 14
	v_add_u32_e32 v243, s7, v7
	v_add_u32_e32 v244, s7, v9
	v_add_u32_e32 v245, s7, v10
	v_add_u32_e32 v246, s7, v11
	ds_read_b64_tr_b16 v[188:189], v243 offset:49152
	ds_read_b64_tr_b16 v[190:191], v243 offset:51200
	ds_read_b64_tr_b16 v[192:193], v244
	ds_read_b64_tr_b16 v[194:195], v244 offset:2048
	ds_read_b64_tr_b16 v[196:197], v245
	ds_read_b64_tr_b16 v[198:199], v245 offset:2048
	ds_read_b64_tr_b16 v[200:201], v246
	ds_read_b64_tr_b16 v[202:203], v246 offset:2048
	v_exp_f32_e32 v228, v96
	v_exp_f32_e32 v229, v97
	v_exp_f32_e32 v230, v98
	v_exp_f32_e32 v231, v99
	v_exp_f32_e32 v232, v100
	v_exp_f32_e32 v233, v101
	v_exp_f32_e32 v234, v102
	v_exp_f32_e32 v187, v103
	v_cvt_pk_bf16_f32 v220, v228, v229
	v_cvt_pk_bf16_f32 v221, v230, v231
	v_cvt_pk_bf16_f32 v222, v232, v233
	v_cvt_pk_bf16_f32 v223, v234, v187
	ds_read_b64_tr_b16 v[204:205], v243 offset:53248
	ds_read_b64_tr_b16 v[206:207], v243 offset:55296
	ds_read_b64_tr_b16 v[208:209], v244 offset:4096
	ds_read_b64_tr_b16 v[210:211], v244 offset:6144
	ds_read_b64_tr_b16 v[212:213], v245 offset:4096
	ds_read_b64_tr_b16 v[214:215], v245 offset:6144
	ds_read_b64_tr_b16 v[216:217], v246 offset:4096
	ds_read_b64_tr_b16 v[218:219], v246 offset:6144
	s_waitcnt lgkmcnt(8)
	v_mfma_f32_32x32x16_bf16 v[80:95], v[188:191], v[220:223], v[80:95]
	ds_read_b64_tr_b16 v[188:189], v243 offset:57344
	ds_read_b64_tr_b16 v[190:191], v243 offset:59392
	v_exp_f32_e32 v247, v104
	v_exp_f32_e32 v248, v105
	v_add_f32_e32 v153, 0, v228
	v_add_f32_e32 v153, v229, v153
	v_mfma_f32_32x32x16_bf16 v[64:79], v[192:195], v[220:223], v[64:79]
	ds_read_b64_tr_b16 v[192:193], v244 offset:8192
	ds_read_b64_tr_b16 v[194:195], v244 offset:10240
	v_exp_f32_e32 v249, v106
	v_exp_f32_e32 v250, v107
	v_add_f32_e32 v153, v230, v153
	v_add_f32_e32 v153, v231, v153
	v_mfma_f32_32x32x16_bf16 v[48:63], v[196:199], v[220:223], v[48:63]
	ds_read_b64_tr_b16 v[196:197], v245 offset:8192
	ds_read_b64_tr_b16 v[198:199], v245 offset:10240
	v_exp_f32_e32 v251, v108
	v_exp_f32_e32 v252, v109
	v_add_f32_e32 v153, v232, v153
	v_add_f32_e32 v153, v233, v153
	v_mfma_f32_32x32x16_bf16 v[32:47], v[200:203], v[220:223], v[32:47]
	ds_read_b64_tr_b16 v[200:201], v246 offset:8192
	ds_read_b64_tr_b16 v[202:203], v246 offset:10240
	v_exp_f32_e32 v253, v110
	v_exp_f32_e32 v254, v111
	v_cvt_pk_bf16_f32 v224, v247, v248
	v_cvt_pk_bf16_f32 v225, v249, v250
	v_cvt_pk_bf16_f32 v226, v251, v252
	v_cvt_pk_bf16_f32 v227, v253, v254
	v_add_f32_e32 v153, v234, v153
	v_add_f32_e32 v153, v187, v153
	s_waitcnt lgkmcnt(8)
	v_mfma_f32_32x32x16_bf16 v[80:95], v[204:207], v[224:227], v[80:95]
	ds_read_b64_tr_b16 v[204:205], v243 offset:61440
	ds_read_b64_tr_b16 v[206:207], v243 offset:63488
	v_exp_f32_e32 v228, v112
	v_exp_f32_e32 v229, v113
	v_add_f32_e32 v153, v247, v153
	v_add_f32_e32 v153, v248, v153
	v_mfma_f32_32x32x16_bf16 v[64:79], v[208:211], v[224:227], v[64:79]
	ds_read_b64_tr_b16 v[208:209], v244 offset:12288
	ds_read_b64_tr_b16 v[210:211], v244 offset:14336
	v_exp_f32_e32 v230, v114
	v_exp_f32_e32 v231, v115
	v_add_f32_e32 v153, v249, v153
	v_add_f32_e32 v153, v250, v153
	v_mfma_f32_32x32x16_bf16 v[48:63], v[212:215], v[224:227], v[48:63]
	ds_read_b64_tr_b16 v[212:213], v245 offset:12288
	ds_read_b64_tr_b16 v[214:215], v245 offset:14336
	v_exp_f32_e32 v232, v116
	v_exp_f32_e32 v233, v117
	v_add_f32_e32 v153, v251, v153
	v_add_f32_e32 v153, v252, v153
	v_mfma_f32_32x32x16_bf16 v[32:47], v[216:219], v[224:227], v[32:47]
	ds_read_b64_tr_b16 v[216:217], v246 offset:12288
	ds_read_b64_tr_b16 v[218:219], v246 offset:14336
	v_exp_f32_e32 v234, v118
	v_exp_f32_e32 v187, v119
	v_cvt_pk_bf16_f32 v220, v228, v229
	v_cvt_pk_bf16_f32 v221, v230, v231
	v_cvt_pk_bf16_f32 v222, v232, v233
	v_cvt_pk_bf16_f32 v223, v234, v187
	v_add_f32_e32 v153, v253, v153
	v_add_f32_e32 v153, v254, v153
	s_waitcnt lgkmcnt(8)
	v_mfma_f32_32x32x16_bf16 v[80:95], v[188:191], v[220:223], v[80:95]
	v_exp_f32_e32 v247, v120
	v_exp_f32_e32 v248, v121
	v_add_f32_e32 v153, v228, v153
	v_add_f32_e32 v153, v229, v153
	v_mfma_f32_32x32x16_bf16 v[64:79], v[192:195], v[220:223], v[64:79]
	v_exp_f32_e32 v249, v122
	v_exp_f32_e32 v250, v123
	v_add_f32_e32 v153, v230, v153
	v_add_f32_e32 v153, v231, v153
	v_mfma_f32_32x32x16_bf16 v[48:63], v[196:199], v[220:223], v[48:63]
	v_exp_f32_e32 v251, v124
	v_exp_f32_e32 v252, v125
	v_add_f32_e32 v153, v232, v153
	v_add_f32_e32 v153, v233, v153
	v_mfma_f32_32x32x16_bf16 v[32:47], v[200:203], v[220:223], v[32:47]
	v_exp_f32_e32 v253, v126
	v_exp_f32_e32 v254, v127
	v_cvt_pk_bf16_f32 v224, v247, v248
	v_cvt_pk_bf16_f32 v225, v249, v250
	v_cvt_pk_bf16_f32 v226, v251, v252
	v_cvt_pk_bf16_f32 v227, v253, v254
	v_add_f32_e32 v153, v234, v153
	v_add_f32_e32 v153, v187, v153
	s_waitcnt lgkmcnt(0)
	v_mfma_f32_32x32x16_bf16 v[80:95], v[204:207], v[224:227], v[80:95]
	v_add_f32_e32 v153, v247, v153
	v_add_f32_e32 v153, v248, v153
	v_mfma_f32_32x32x16_bf16 v[64:79], v[208:211], v[224:227], v[64:79]
	v_add_f32_e32 v153, v249, v153
	v_add_f32_e32 v153, v250, v153
	v_mfma_f32_32x32x16_bf16 v[48:63], v[212:215], v[224:227], v[48:63]
	v_add_f32_e32 v153, v251, v153
	v_add_f32_e32 v153, v252, v153
	v_mfma_f32_32x32x16_bf16 v[32:47], v[216:219], v[224:227], v[32:47]
	v_add_f32_e32 v153, v253, v153
	v_add_f32_e32 v153, v254, v153
	v_add_f32_e32 v6, v6, v153
	s_add_u32 s72, s72, 0x20000
	s_addc_u32 s73, s73, 0
	s_add_i32 s95, s95, 1
	s_mov_b32 s71, s8
	s_mov_b32 s8, s78
	s_mov_b32 s78, s88
	s_mov_b32 s88, s71
	s_sub_i32 s101, s101, 1
	s_cmp_lg_u32 s101, 0
	s_cbranch_scc1 .Latt_flA_top
	s_waitcnt vmcnt(4) lgkmcnt(0)
	s_barrier
	s_lshl_b32 s4, s100, 6
	s_sub_i32 s33, s33, s4
	s_sub_i32 s93, s93, s4
	s_sub_u32 s90, s90, s4
	s_subb_u32 s91, s91, 0
	v_add_u32_e32 v179, s4, v179
	s_branch .Latt_slow

.LBB0_1330:
	s_cmp_eq_u32 s69, 0
	s_cselect_b64 s[2:3], -1, 0
	s_and_b64 s[0:1], s[0:1], s[2:3]
	s_andn2_b64 vcc, exec, s[0:1]
	s_waitcnt lgkmcnt(0)
	s_barrier
	s_cbranch_vccnz .LBB0_1332
	ds_read2st64_b32 v[4:5], v0 offset1:1
	ds_read2st64_b32 v[6:7], v0 offset0:2 offset1:3
	ds_read2st64_b32 v[14:15], v0 offset0:4 offset1:5
	ds_read2st64_b32 v[18:19], v0 offset0:6 offset1:7
	v_mov_b32_e32 v148, v80
	v_readlane_b32 s0, v238, 50
	s_waitcnt lgkmcnt(3)
	v_mov_b32_e32 v3, v4
	v_pk_mul_f32 v[10:11], v[148:149], v[2:3]
	v_mov_b32_e32 v148, v81
	v_mov_b32_e32 v3, v5
	v_pk_mul_f32 v[4:5], v[148:149], v[2:3]
	v_mov_b32_e32 v148, v82
	s_waitcnt lgkmcnt(2)
	v_mov_b32_e32 v3, v6
	v_sub_f32_e32 v9, v10, v11
	v_sub_f32_e32 v10, v4, v5
	v_pk_mul_f32 v[4:5], v[148:149], v[2:3]
	v_mov_b32_e32 v148, v83
	v_mov_b32_e32 v3, v7
	v_sub_f32_e32 v11, v4, v5
	v_pk_mul_f32 v[4:5], v[148:149], v[2:3]
	v_mov_b32_e32 v148, v84
	s_waitcnt lgkmcnt(1)
	v_mov_b32_e32 v3, v14
	v_sub_f32_e32 v13, v4, v5
	v_pk_mul_f32 v[4:5], v[148:149], v[2:3]
	v_mov_b32_e32 v148, v85
	v_mov_b32_e32 v3, v15
	v_sub_f32_e32 v12, v4, v5
	v_pk_mul_f32 v[4:5], v[148:149], v[2:3]
	v_mov_b32_e32 v148, v86
	s_waitcnt lgkmcnt(0)
	v_mov_b32_e32 v3, v18
	v_sub_f32_e32 v14, v4, v5
	v_pk_mul_f32 v[4:5], v[148:149], v[2:3]
	v_mov_b32_e32 v148, v87
	v_mov_b32_e32 v3, v19
	v_sub_f32_e32 v15, v4, v5
	v_pk_mul_f32 v[4:5], v[148:149], v[2:3]
	v_mov_b32_e32 v148, v88
	v_sub_f32_e32 v17, v4, v5
	ds_read2st64_b32 v[4:5], v0 offset0:8 offset1:9
	ds_read2st64_b32 v[6:7], v0 offset0:10 offset1:11
	ds_read2st64_b32 v[24:25], v0 offset0:12 offset1:13
	ds_read2st64_b32 v[26:27], v0 offset0:14 offset1:15
	s_waitcnt lgkmcnt(3)
	v_mov_b32_e32 v3, v4
	v_pk_mul_f32 v[18:19], v[148:149], v[2:3]
	v_mov_b32_e32 v148, v89
	v_mov_b32_e32 v3, v5
	v_pk_mul_f32 v[4:5], v[148:149], v[2:3]
	v_mov_b32_e32 v148, v90
	s_waitcnt lgkmcnt(2)
	v_mov_b32_e32 v3, v6
	v_sub_f32_e32 v18, v18, v19
	v_sub_f32_e32 v19, v4, v5
	v_pk_mul_f32 v[4:5], v[148:149], v[2:3]
	v_mov_b32_e32 v148, v91
	v_mov_b32_e32 v3, v7
	v_sub_f32_e32 v20, v4, v5
	v_pk_mul_f32 v[4:5], v[148:149], v[2:3]
	v_mov_b32_e32 v148, v92
	s_waitcnt lgkmcnt(1)
	v_mov_b32_e32 v3, v24
	v_sub_f32_e32 v22, v4, v5
	v_pk_mul_f32 v[4:5], v[148:149], v[2:3]
	v_mov_b32_e32 v148, v93
	v_mov_b32_e32 v3, v25
	v_sub_f32_e32 v21, v4, v5
	v_pk_mul_f32 v[4:5], v[148:149], v[2:3]
	v_mov_b32_e32 v148, v94
	s_waitcnt lgkmcnt(0)
	v_mov_b32_e32 v3, v26
	v_sub_f32_e32 v23, v4, v5
	v_pk_mul_f32 v[4:5], v[148:149], v[2:3]
	v_mov_b32_e32 v148, v95
	v_mov_b32_e32 v3, v27
	v_sub_f32_e32 v24, v4, v5
	v_pk_mul_f32 v[4:5], v[148:149], v[2:3]
	v_mov_b32_e32 v148, v64
	v_sub_f32_e32 v25, v4, v5
	ds_read2st64_b32 v[4:5], v0 offset0:16 offset1:17
	ds_read2st64_b32 v[6:7], v0 offset0:18 offset1:19
	ds_read2st64_b32 v[80:81], v0 offset0:20 offset1:21
	ds_read2st64_b32 v[82:83], v0 offset0:22 offset1:23
	s_waitcnt lgkmcnt(3)
	v_mov_b32_e32 v3, v4
	v_pk_mul_f32 v[26:27], v[148:149], v[2:3]
	v_mov_b32_e32 v148, v65
	v_mov_b32_e32 v3, v5
	v_pk_mul_f32 v[4:5], v[148:149], v[2:3]
	v_mov_b32_e32 v148, v66
	s_waitcnt lgkmcnt(2)
	v_mov_b32_e32 v3, v6
	v_sub_f32_e32 v26, v26, v27
	v_sub_f32_e32 v27, v4, v5
	v_pk_mul_f32 v[4:5], v[148:149], v[2:3]
	v_mov_b32_e32 v148, v67
	v_mov_b32_e32 v3, v7
	v_sub_f32_e32 v28, v4, v5
	v_pk_mul_f32 v[4:5], v[148:149], v[2:3]
	v_mov_b32_e32 v148, v68
	s_waitcnt lgkmcnt(1)
	v_mov_b32_e32 v3, v80
	v_sub_f32_e32 v30, v4, v5
	v_pk_mul_f32 v[4:5], v[148:149], v[2:3]
	v_mov_b32_e32 v148, v69
	v_mov_b32_e32 v3, v81
	v_sub_f32_e32 v29, v4, v5
	v_pk_mul_f32 v[4:5], v[148:149], v[2:3]
	v_mov_b32_e32 v148, v70
	s_waitcnt lgkmcnt(0)
	v_mov_b32_e32 v3, v82
	v_sub_f32_e32 v31, v4, v5
	v_pk_mul_f32 v[4:5], v[148:149], v[2:3]
	v_mov_b32_e32 v148, v71
	v_mov_b32_e32 v3, v83
	v_sub_f32_e32 v64, v4, v5
	v_pk_mul_f32 v[4:5], v[148:149], v[2:3]
	v_mov_b32_e32 v148, v72
	v_sub_f32_e32 v65, v4, v5
	ds_read2st64_b32 v[4:5], v0 offset0:24 offset1:25
	ds_read2st64_b32 v[6:7], v0 offset0:26 offset1:27
	ds_read2st64_b32 v[80:81], v0 offset0:28 offset1:29
	ds_read2st64_b32 v[82:83], v0 offset0:30 offset1:31
	s_waitcnt lgkmcnt(3)
	v_mov_b32_e32 v3, v4
	v_pk_mul_f32 v[66:67], v[148:149], v[2:3]
	v_mov_b32_e32 v148, v73
	v_mov_b32_e32 v3, v5
	v_pk_mul_f32 v[4:5], v[148:149], v[2:3]
	v_mov_b32_e32 v148, v74
	s_waitcnt lgkmcnt(2)
	v_mov_b32_e32 v3, v6
	v_sub_f32_e32 v66, v66, v67
	v_sub_f32_e32 v67, v4, v5
	v_pk_mul_f32 v[4:5], v[148:149], v[2:3]
	v_mov_b32_e32 v148, v75
	v_mov_b32_e32 v3, v7
	v_sub_f32_e32 v68, v4, v5
	v_pk_mul_f32 v[4:5], v[148:149], v[2:3]
	v_mov_b32_e32 v148, v76
	s_waitcnt lgkmcnt(1)
	v_mov_b32_e32 v3, v80
	v_sub_f32_e32 v70, v4, v5
	v_pk_mul_f32 v[4:5], v[148:149], v[2:3]
	v_mov_b32_e32 v148, v77
	v_mov_b32_e32 v3, v81
	v_sub_f32_e32 v69, v4, v5
	v_pk_mul_f32 v[4:5], v[148:149], v[2:3]
	v_mov_b32_e32 v148, v78
	s_waitcnt lgkmcnt(0)
	v_mov_b32_e32 v3, v82
	v_sub_f32_e32 v71, v4, v5
	v_pk_mul_f32 v[4:5], v[148:149], v[2:3]
	v_mov_b32_e32 v148, v79
	v_mov_b32_e32 v3, v83
	v_sub_f32_e32 v72, v4, v5
	v_pk_mul_f32 v[4:5], v[148:149], v[2:3]
	v_mov_b32_e32 v148, v48
	v_sub_f32_e32 v73, v4, v5
	ds_read2st64_b32 v[4:5], v0 offset0:32 offset1:33
	ds_read2st64_b32 v[6:7], v0 offset0:34 offset1:35
	ds_read2st64_b32 v[74:75], v0 offset0:36 offset1:37
	ds_read2st64_b32 v[76:77], v0 offset0:38 offset1:39
	s_waitcnt lgkmcnt(3)
	v_mov_b32_e32 v3, v4
	v_pk_mul_f32 v[78:79], v[148:149], v[2:3]
	v_mov_b32_e32 v148, v49
	v_mov_b32_e32 v3, v5
	v_pk_mul_f32 v[4:5], v[148:149], v[2:3]
	v_mov_b32_e32 v148, v50
	s_waitcnt lgkmcnt(2)
	v_mov_b32_e32 v3, v6
	v_sub_f32_e32 v78, v78, v79
	v_sub_f32_e32 v79, v4, v5
	v_pk_mul_f32 v[4:5], v[148:149], v[2:3]
	v_mov_b32_e32 v148, v51
	v_mov_b32_e32 v3, v7
	v_sub_f32_e32 v80, v4, v5
	v_pk_mul_f32 v[4:5], v[148:149], v[2:3]
	v_mov_b32_e32 v148, v52
	s_waitcnt lgkmcnt(1)
	v_mov_b32_e32 v3, v74
	v_sub_f32_e32 v81, v4, v5
	v_pk_mul_f32 v[4:5], v[148:149], v[2:3]
	v_mov_b32_e32 v148, v53
	v_mov_b32_e32 v3, v75
	v_sub_f32_e32 v74, v4, v5
	v_pk_mul_f32 v[4:5], v[148:149], v[2:3]
	v_mov_b32_e32 v148, v54
	s_waitcnt lgkmcnt(0)
	v_mov_b32_e32 v3, v76
	v_sub_f32_e32 v75, v4, v5
	v_pk_mul_f32 v[4:5], v[148:149], v[2:3]
	v_mov_b32_e32 v148, v55
	v_mov_b32_e32 v3, v77
	v_sub_f32_e32 v54, v4, v5
	v_pk_mul_f32 v[4:5], v[148:149], v[2:3]
	v_mov_b32_e32 v148, v56
	v_sub_f32_e32 v55, v4, v5
	ds_read2st64_b32 v[4:5], v0 offset0:40 offset1:41
	ds_read2st64_b32 v[6:7], v0 offset0:42 offset1:43
	ds_read2st64_b32 v[48:49], v0 offset0:44 offset1:45
	ds_read2st64_b32 v[50:51], v0 offset0:46 offset1:47
	s_waitcnt lgkmcnt(3)
	v_mov_b32_e32 v3, v4
	v_pk_mul_f32 v[52:53], v[148:149], v[2:3]
	v_mov_b32_e32 v148, v57
	v_mov_b32_e32 v3, v5
	v_pk_mul_f32 v[4:5], v[148:149], v[2:3]
	v_mov_b32_e32 v148, v58
	s_waitcnt lgkmcnt(2)
	v_mov_b32_e32 v3, v6
	v_sub_f32_e32 v57, v4, v5
	v_pk_mul_f32 v[4:5], v[148:149], v[2:3]
	v_mov_b32_e32 v148, v59
	v_mov_b32_e32 v3, v7
	v_sub_f32_e32 v58, v4, v5
	v_pk_mul_f32 v[4:5], v[148:149], v[2:3]
	v_mov_b32_e32 v148, v60
	s_waitcnt lgkmcnt(1)
	v_mov_b32_e32 v3, v48
	v_sub_f32_e32 v59, v4, v5
	v_pk_mul_f32 v[4:5], v[148:149], v[2:3]
	v_mov_b32_e32 v148, v61
	v_mov_b32_e32 v3, v49
	v_sub_f32_e32 v60, v4, v5
	v_pk_mul_f32 v[4:5], v[148:149], v[2:3]
	v_mov_b32_e32 v148, v62
	s_waitcnt lgkmcnt(0)
	v_mov_b32_e32 v3, v50
	v_sub_f32_e32 v61, v4, v5
	v_pk_mul_f32 v[4:5], v[148:149], v[2:3]
	v_mov_b32_e32 v148, v63
	v_mov_b32_e32 v3, v51
	v_sub_f32_e32 v62, v4, v5
	v_pk_mul_f32 v[4:5], v[148:149], v[2:3]
	v_mov_b32_e32 v148, v32
	v_sub_f32_e32 v63, v4, v5
	ds_read2st64_b32 v[4:5], v0 offset0:48 offset1:49
	ds_read2st64_b32 v[6:7], v0 offset0:50 offset1:51
	ds_read2st64_b32 v[48:49], v0 offset0:52 offset1:53
	ds_read2st64_b32 v[50:51], v0 offset0:54 offset1:55
	v_sub_f32_e32 v56, v52, v53
	s_waitcnt lgkmcnt(3)
	v_mov_b32_e32 v3, v4
	v_pk_mul_f32 v[52:53], v[148:149], v[2:3]
	v_mov_b32_e32 v148, v33
	v_mov_b32_e32 v3, v5
	v_pk_mul_f32 v[4:5], v[148:149], v[2:3]
	v_mov_b32_e32 v148, v34
	s_waitcnt lgkmcnt(2)
	v_mov_b32_e32 v3, v6
	v_sub_f32_e32 v52, v52, v53
	v_sub_f32_e32 v53, v4, v5
	v_pk_mul_f32 v[4:5], v[148:149], v[2:3]
	v_mov_b32_e32 v148, v35
	v_mov_b32_e32 v3, v7
	v_sub_f32_e32 v76, v4, v5
	v_pk_mul_f32 v[4:5], v[148:149], v[2:3]
	v_mov_b32_e32 v148, v36
	s_waitcnt lgkmcnt(1)
	v_mov_b32_e32 v3, v48
	v_sub_f32_e32 v77, v4, v5
	v_pk_mul_f32 v[4:5], v[148:149], v[2:3]
	v_mov_b32_e32 v148, v37
	v_mov_b32_e32 v3, v49
	v_sub_f32_e32 v48, v4, v5
	v_pk_mul_f32 v[4:5], v[148:149], v[2:3]
	v_mov_b32_e32 v148, v38
	s_waitcnt lgkmcnt(0)
	v_mov_b32_e32 v3, v50
	v_sub_f32_e32 v49, v4, v5
	v_pk_mul_f32 v[4:5], v[148:149], v[2:3]
	v_mov_b32_e32 v148, v39
	v_mov_b32_e32 v3, v51
	v_sub_f32_e32 v38, v4, v5
	v_pk_mul_f32 v[4:5], v[148:149], v[2:3]
	v_mov_b32_e32 v148, v40
	v_sub_f32_e32 v39, v4, v5
	ds_read2st64_b32 v[4:5], v0 offset0:56 offset1:57
	ds_read2st64_b32 v[6:7], v0 offset0:58 offset1:59
	ds_read2st64_b32 v[32:33], v0 offset0:60 offset1:61
	ds_read2st64_b32 v[34:35], v0 offset0:62 offset1:63
	v_mul_f32_e32 v0, v9, v9
	v_fmac_f32_e32 v0, v10, v10
	v_fmac_f32_e32 v0, v11, v11
	v_fmac_f32_e32 v0, v13, v13
	v_fmac_f32_e32 v0, v12, v12
	v_fmac_f32_e32 v0, v14, v14
	v_fmac_f32_e32 v0, v15, v15
	v_fmac_f32_e32 v0, v17, v17
	v_fmac_f32_e32 v0, v18, v18
	v_fmac_f32_e32 v0, v19, v19
	v_fmac_f32_e32 v0, v20, v20
	v_fmac_f32_e32 v0, v22, v22
	v_fmac_f32_e32 v0, v21, v21
	v_fmac_f32_e32 v0, v23, v23
	v_fmac_f32_e32 v0, v24, v24
	v_fmac_f32_e32 v0, v25, v25
	v_fmac_f32_e32 v0, v26, v26
	v_fmac_f32_e32 v0, v27, v27
	v_fmac_f32_e32 v0, v28, v28
	v_fmac_f32_e32 v0, v30, v30
	v_fmac_f32_e32 v0, v29, v29
	v_fmac_f32_e32 v0, v31, v31
	v_fmac_f32_e32 v0, v64, v64
	v_fmac_f32_e32 v0, v65, v65
	v_fmac_f32_e32 v0, v66, v66
	v_fmac_f32_e32 v0, v67, v67
	v_fmac_f32_e32 v0, v68, v68
	v_fmac_f32_e32 v0, v70, v70
	v_fmac_f32_e32 v0, v69, v69
	v_fmac_f32_e32 v0, v71, v71
	v_fmac_f32_e32 v0, v72, v72
	v_fmac_f32_e32 v0, v73, v73
	v_fmac_f32_e32 v0, v78, v78
	v_fmac_f32_e32 v0, v79, v79
	v_fmac_f32_e32 v0, v80, v80
	v_fmac_f32_e32 v0, v81, v81
	v_fmac_f32_e32 v0, v74, v74
	v_fmac_f32_e32 v0, v75, v75
	v_fmac_f32_e32 v0, v54, v54
	v_fmac_f32_e32 v0, v55, v55
	v_fmac_f32_e32 v0, v56, v56
	v_fmac_f32_e32 v0, v57, v57
	v_fmac_f32_e32 v0, v58, v58
	v_fmac_f32_e32 v0, v59, v59
	v_fmac_f32_e32 v0, v60, v60
	v_fmac_f32_e32 v0, v61, v61
	v_fmac_f32_e32 v0, v62, v62
	v_fmac_f32_e32 v0, v63, v63
	v_fmac_f32_e32 v0, v52, v52
	v_fmac_f32_e32 v0, v53, v53
	v_fmac_f32_e32 v0, v76, v76
	v_fmac_f32_e32 v0, v77, v77
	s_waitcnt lgkmcnt(3)
	v_mov_b32_e32 v3, v4
	v_fmac_f32_e32 v0, v48, v48
	v_pk_mul_f32 v[36:37], v[148:149], v[2:3]
	v_mov_b32_e32 v148, v41
	v_mov_b32_e32 v3, v5
	v_fmac_f32_e32 v0, v49, v49
	v_pk_mul_f32 v[4:5], v[148:149], v[2:3]
	v_fmac_f32_e32 v0, v38, v38
	v_sub_f32_e32 v40, v36, v37
	v_sub_f32_e32 v41, v4, v5
	s_waitcnt lgkmcnt(2)
	v_pk_mul_f32 v[4:5], v[150:151], v[6:7]
	v_fmac_f32_e32 v0, v39, v39
	v_pk_fma_f32 v[6:7], v[42:43], v[2:3], v[4:5] op_sel_hi:[1,0,1] neg_lo:[0,0,1] neg_hi:[0,0,1]
	v_fmac_f32_e32 v0, v40, v40
	v_pk_mul_f32 v[36:37], v[6:7], v[6:7]
	s_waitcnt lgkmcnt(1)
	v_pk_mul_f32 v[4:5], v[150:151], v[32:33]
	v_fmac_f32_e32 v0, v41, v41
	v_pk_fma_f32 v[4:5], v[44:45], v[2:3], v[4:5] op_sel_hi:[1,0,1] neg_lo:[0,0,1] neg_hi:[0,0,1]
	v_add_f32_e32 v0, v0, v36
	v_pk_mul_f32 v[32:33], v[4:5], v[4:5]
	s_waitcnt lgkmcnt(0)
	v_pk_mul_f32 v[34:35], v[150:151], v[34:35]
	v_add_f32_e32 v0, v0, v37
	v_pk_fma_f32 v[2:3], v[46:47], v[2:3], v[34:35] op_sel_hi:[1,0,1] neg_lo:[0,0,1] neg_hi:[0,0,1]
	v_add_f32_e32 v0, v0, v32
	v_pk_mul_f32 v[34:35], v[2:3], v[2:3]
	v_add_f32_e32 v0, v0, v33
	v_add_f32_e32 v0, v0, v34
	v_add_f32_e32 v0, v0, v35
	ds_bpermute_b32 v32, v186, v0
	s_waitcnt lgkmcnt(0)
	v_add_f32_e32 v0, v0, v32
	v_fmamk_f32 v0, v0, 0x3c000000, v157
	v_rsq_f32_e32 v34, v0
	v_or_b32_e32 v32, s0, v162
	v_ashrrev_i32_e32 v33, 31, v32
	v_lshlrev_b64 v[32:33], 11, v[32:33]
	v_lshl_add_u64 v[32:33], s[6:7], 0, v[32:33]
	v_lshlrev_b32_e32 v0, 1, v8
	v_lshl_add_u64 v[32:33], v[32:33], 0, v[0:1]
	v_and_b32_e32 v104, 32, v160
	v_lshrrev_b32_e32 v104, 2, v104
	v_mov_b32_e32 v105, 0
	v_lshl_add_u64 v[32:33], v[32:33], 0, v[104:105]
	v_mul_f32_e32 v106, v9, v34
	v_mul_f32_e32 v107, v10, v34
	v_cvt_pk_bf16_f32 v96, v106, v107
	v_mul_f32_e32 v106, v11, v34
	v_mul_f32_e32 v107, v13, v34
	v_cvt_pk_bf16_f32 v97, v106, v107
	v_mul_f32_e32 v106, v12, v34
	v_mul_f32_e32 v107, v14, v34
	v_cvt_pk_bf16_f32 v98, v106, v107
	v_mul_f32_e32 v106, v15, v34
	v_mul_f32_e32 v107, v17, v34
	v_cvt_pk_bf16_f32 v99, v106, v107
	s_nop 1
	v_permlane32_swap_b32_e32 v96, v98
	v_permlane32_swap_b32_e32 v97, v99
	global_store_dwordx4 v[32:33], v[96:99], off
	v_mul_f32_e32 v106, v18, v34
	v_mul_f32_e32 v107, v19, v34
	v_cvt_pk_bf16_f32 v100, v106, v107
	v_mul_f32_e32 v106, v20, v34
	v_mul_f32_e32 v107, v22, v34
	v_cvt_pk_bf16_f32 v101, v106, v107
	v_mul_f32_e32 v106, v21, v34
	v_mul_f32_e32 v107, v23, v34
	v_cvt_pk_bf16_f32 v102, v106, v107
	v_mul_f32_e32 v106, v24, v34
	v_mul_f32_e32 v107, v25, v34
	v_cvt_pk_bf16_f32 v103, v106, v107
	s_nop 1
	v_permlane32_swap_b32_e32 v100, v102
	v_permlane32_swap_b32_e32 v101, v103
	global_store_dwordx4 v[32:33], v[100:103], off offset:32
	v_mul_f32_e32 v106, v26, v34
	v_mul_f32_e32 v107, v27, v34
	v_cvt_pk_bf16_f32 v96, v106, v107
	v_mul_f32_e32 v106, v28, v34
	v_mul_f32_e32 v107, v30, v34
	v_cvt_pk_bf16_f32 v97, v106, v107
	v_mul_f32_e32 v106, v29, v34
	v_mul_f32_e32 v107, v31, v34
	v_cvt_pk_bf16_f32 v98, v106, v107
	v_mul_f32_e32 v106, v64, v34
	v_mul_f32_e32 v107, v65, v34
	v_cvt_pk_bf16_f32 v99, v106, v107
	s_nop 1
	v_permlane32_swap_b32_e32 v96, v98
	v_permlane32_swap_b32_e32 v97, v99
	global_store_dwordx4 v[32:33], v[96:99], off offset:64
	v_mul_f32_e32 v106, v66, v34
	v_mul_f32_e32 v107, v67, v34
	v_cvt_pk_bf16_f32 v100, v106, v107
	v_mul_f32_e32 v106, v68, v34
	v_mul_f32_e32 v107, v70, v34
	v_cvt_pk_bf16_f32 v101, v106, v107
	v_mul_f32_e32 v106, v69, v34
	v_mul_f32_e32 v107, v71, v34
	v_cvt_pk_bf16_f32 v102, v106, v107
	v_mul_f32_e32 v106, v72, v34
	v_mul_f32_e32 v107, v73, v34
	v_cvt_pk_bf16_f32 v103, v106, v107
	s_nop 1
	v_permlane32_swap_b32_e32 v100, v102
	v_permlane32_swap_b32_e32 v101, v103
	global_store_dwordx4 v[32:33], v[100:103], off offset:96
	v_mul_f32_e32 v106, v78, v34
	v_mul_f32_e32 v107, v79, v34
	v_cvt_pk_bf16_f32 v96, v106, v107
	v_mul_f32_e32 v106, v80, v34
	v_mul_f32_e32 v107, v81, v34
	v_cvt_pk_bf16_f32 v97, v106, v107
	v_mul_f32_e32 v106, v74, v34
	v_mul_f32_e32 v107, v75, v34
	v_cvt_pk_bf16_f32 v98, v106, v107
	v_mul_f32_e32 v106, v54, v34
	v_mul_f32_e32 v107, v55, v34
	v_cvt_pk_bf16_f32 v99, v106, v107
	s_nop 1
	v_permlane32_swap_b32_e32 v96, v98
	v_permlane32_swap_b32_e32 v97, v99
	global_store_dwordx4 v[32:33], v[96:99], off offset:128
	v_mul_f32_e32 v106, v56, v34
	v_mul_f32_e32 v107, v57, v34
	v_cvt_pk_bf16_f32 v100, v106, v107
	v_mul_f32_e32 v106, v58, v34
	v_mul_f32_e32 v107, v59, v34
	v_cvt_pk_bf16_f32 v101, v106, v107
	v_mul_f32_e32 v106, v60, v34
	v_mul_f32_e32 v107, v61, v34
	v_cvt_pk_bf16_f32 v102, v106, v107
	v_mul_f32_e32 v106, v62, v34
	v_mul_f32_e32 v107, v63, v34
	v_cvt_pk_bf16_f32 v103, v106, v107
	s_nop 1
	v_permlane32_swap_b32_e32 v100, v102
	v_permlane32_swap_b32_e32 v101, v103
	global_store_dwordx4 v[32:33], v[100:103], off offset:160
	v_mul_f32_e32 v106, v52, v34
	v_mul_f32_e32 v107, v53, v34
	v_cvt_pk_bf16_f32 v96, v106, v107
	v_mul_f32_e32 v106, v76, v34
	v_mul_f32_e32 v107, v77, v34
	v_cvt_pk_bf16_f32 v97, v106, v107
	v_mul_f32_e32 v106, v48, v34
	v_mul_f32_e32 v107, v49, v34
	v_cvt_pk_bf16_f32 v98, v106, v107
	v_mul_f32_e32 v106, v38, v34
	v_mul_f32_e32 v107, v39, v34
	v_cvt_pk_bf16_f32 v99, v106, v107
	s_nop 1
	v_permlane32_swap_b32_e32 v96, v98
	v_permlane32_swap_b32_e32 v97, v99
	global_store_dwordx4 v[32:33], v[96:99], off offset:192
	v_mul_f32_e32 v106, v40, v34
	v_mul_f32_e32 v107, v41, v34
	v_cvt_pk_bf16_f32 v100, v106, v107
	v_mul_f32_e32 v106, v6, v34
	v_mul_f32_e32 v107, v7, v34
	v_cvt_pk_bf16_f32 v101, v106, v107
	v_mul_f32_e32 v106, v4, v34
	v_mul_f32_e32 v107, v5, v34
	v_cvt_pk_bf16_f32 v102, v106, v107
	v_mul_f32_e32 v106, v2, v34
	v_mul_f32_e32 v107, v3, v34
	v_cvt_pk_bf16_f32 v103, v106, v107
	s_nop 1
	v_permlane32_swap_b32_e32 v100, v102
	v_permlane32_swap_b32_e32 v101, v103
	global_store_dwordx4 v[32:33], v[100:103], off offset:224
